# grid barrier: skip buffer_wbl2 after phases whose stores are all sc1 write-through (down, out-proj, last gate|up)
# baseline (speedup 1.0000x reference)
.LBB0_1404:
	s_andn2_saveexec_b64 s[8:9], s[8:9]
	s_cbranch_execz .LBB0_1424
	s_mov_b64 s[8:9], exec
	s_mov_b32 vcc_lo, 0x1a2488
	s_lshr_b32 vcc_lo, vcc_lo, s68
	s_bitcmp1_b32 vcc_lo, 0
	s_cbranch_scc1 .Lskip_wbl2
	buffer_wbl2 sc1
.Lskip_wbl2:
	s_waitcnt lgkmcnt(0)
	s_waitcnt vmcnt(0)
	v_mbcnt_lo_u32_b32 v1, s8, 0
	v_mbcnt_hi_u32_b32 v1, s9, v1
	v_cmp_eq_u32_e32 vcc, 0, v1
	s_and_saveexec_b64 s[10:11], vcc
	s_cbranch_execz .LBB0_1407
	s_bcnt1_i32_b64 s8, s[8:9]
	v_mov_b32_e32 v2, s8
	v_mov_b32_e32 v3, 0x629f000
	global_atomic_add v2, v3, v2, s[4:5] offset:2048 sc0
